# block-id permutation variant: transposed 8x8 patch coordinates
# baseline (speedup 1.0000x reference)
.Lrole_done:
	s_lshl_b32 s98, s98, 1
	s_or_b32 s99, s99, s98
	s_lshl_b32 s100, s100, 2
	s_or_b32 s101, s99, s100
	v_readlane_b32 s98, v252, 0
	s_lshr_b32 s98, s98, 3
	s_and_b32 s98, s98, 0xff
	s_lshl_b32 s98, s98, 8
	s_or_b32 s101, s101, s98
	v_readlane_b32 s98, v252, 0
	s_lshr_b32 s99, s98, 3
	s_and_b32 s98, s98, 7
	s_and_b32 s100, s99, 7
	s_lshl_b32 s100, s100, 3
	s_lshr_b32 s99, s99, 3
	s_or_b32 s99, s99, s100
	s_lshl_b32 s99, s99, 3
	s_or_b32 s98, s98, s99
	s_nop 0
	v_writelane_b32 v252, s98, 0
	s_load_dwordx2 s[52:53], s[0:1], 0x210
	s_waitcnt lgkmcnt(0)
	s_cmp_ge_i32 s52, s53
	s_cbranch_scc1 .Lend_near
	s_load_dwordx2 s[22:23], s[0:1], 0x1a8
	s_load_dwordx16 s[56:71], s[0:1], 0x0
	s_load_dwordx16 s[36:51], s[0:1], 0x40
	s_load_dwordx16 s[4:19], s[0:1], 0x80
	v_lshrrev_b32_e32 v1, 20, v0
	v_lshrrev_b32_e32 v0, 10, v0
	v_or_b32_e32 v0, v0, v1
	s_mov_b32 s97, 0
	s_waitcnt lgkmcnt(0)
	v_writelane_b32 v252, s4, 5
	s_movk_i32 s55, 0x4000
	v_mov_b32_e32 v2, 0
	v_writelane_b32 v252, s5, 6
	v_writelane_b32 v252, s6, 7
	v_writelane_b32 v252, s7, 8
	v_writelane_b32 v252, s8, 9
	v_writelane_b32 v252, s9, 10
	v_writelane_b32 v252, s10, 11
	v_writelane_b32 v252, s11, 12
	v_writelane_b32 v252, s12, 13
	v_writelane_b32 v252, s13, 14
	v_writelane_b32 v252, s14, 15
	v_writelane_b32 v252, s15, 16
	v_writelane_b32 v252, s16, 17
	v_writelane_b32 v252, s17, 18
	v_writelane_b32 v252, s18, 19
	v_writelane_b32 v252, s19, 20
	s_load_dwordx16 s[4:19], s[0:1], 0xc0
	s_mov_b32 s28, 0x10000
	v_mov_b32_e32 v198, 0x358637bd
	s_movk_i32 s96, 0x43ff
	s_mov_b32 s29, 0x20000
	s_waitcnt lgkmcnt(0)
	v_writelane_b32 v252, s4, 21
	v_mov_b32_e32 v199, 0x10000
	s_movk_i32 s33, 0x110
	v_writelane_b32 v252, s5, 22
	v_writelane_b32 v252, s6, 23
	v_writelane_b32 v252, s7, 24
	v_writelane_b32 v252, s8, 25
	v_writelane_b32 v252, s9, 26
	v_writelane_b32 v252, s10, 27
	v_writelane_b32 v252, s11, 28
	v_writelane_b32 v252, s12, 29
	v_writelane_b32 v252, s13, 30
	v_writelane_b32 v252, s14, 31
	v_writelane_b32 v252, s15, 32
	v_writelane_b32 v252, s16, 33
	v_writelane_b32 v252, s17, 34
	v_writelane_b32 v252, s18, 35
	v_writelane_b32 v252, s19, 36
	s_load_dwordx16 s[4:19], s[0:1], 0x100
	v_mov_b32_e32 v201, 0x3ecc95a3
	v_mov_b64_e32 v[212:213], 0xe00
	v_mov_b64_e32 v[196:197], 0x3600
	v_mov_b32_e32 v204, 0x7f800000
	s_waitcnt lgkmcnt(0)
	v_writelane_b32 v252, s4, 37
	v_mov_b32_e32 v206, 0x41b17218
	v_mov_b32_e32 v136, 0x3f317218
	v_writelane_b32 v252, s5, 38
	v_writelane_b32 v252, s6, 39
	v_writelane_b32 v252, s7, 40
	v_writelane_b32 v252, s8, 41
	v_writelane_b32 v252, s9, 42
	v_writelane_b32 v252, s10, 43
	v_writelane_b32 v252, s11, 44
	v_writelane_b32 v252, s12, 45
	v_writelane_b32 v252, s13, 46
	v_writelane_b32 v252, s14, 47
	v_writelane_b32 v252, s15, 48
	v_writelane_b32 v252, s16, 49
	v_writelane_b32 v252, s17, 50
	v_writelane_b32 v252, s18, 51
	v_writelane_b32 v252, s19, 52
	s_load_dwordx16 s[72:87], s[0:1], 0x140
	s_load_dwordx16 s[4:19], s[0:1], 0x1b0
	v_mov_b32_e32 v203, 0x7fc00000
	v_mov_b32_e32 v195, 0xff800000
	v_mov_b32_e32 v205, 0xe400
	v_mov_b32_e32 v200, 0x9f00
	s_waitcnt lgkmcnt(0)
	v_writelane_b32 v252, s4, 53
	v_mov_b32_e32 v207, 0x42800000
	s_nop 0
	v_writelane_b32 v252, s5, 54
	v_writelane_b32 v252, s6, 55
	v_writelane_b32 v252, s7, 56
	v_writelane_b32 v253, s15, 0
	v_writelane_b32 v252, s8, 57
	v_writelane_b32 v253, s16, 1
	v_writelane_b32 v252, s9, 58
	v_writelane_b32 v253, s17, 2
	v_writelane_b32 v252, s10, 59
	v_writelane_b32 v253, s18, 3
	v_writelane_b32 v252, s11, 60
	v_writelane_b32 v253, s19, 4
	s_load_dwordx8 s[4:11], s[0:1], 0x1f0
	s_add_u32 s0, s0, 0x218
	s_addc_u32 s1, s1, 0
	v_writelane_b32 v252, s12, 61
	v_writelane_b32 v252, s13, 62
	s_waitcnt lgkmcnt(0)
	v_writelane_b32 v253, s4, 5
	v_writelane_b32 v252, s14, 63
	s_nop 0
	v_writelane_b32 v253, s5, 6
	v_writelane_b32 v253, s6, 7
	v_writelane_b32 v253, s7, 8
	v_writelane_b32 v253, s8, 9
	v_writelane_b32 v253, s9, 10
	v_writelane_b32 v253, s10, 11
	v_writelane_b32 v253, s11, 12
	v_writelane_b32 v253, s0, 13
	s_nop 1
	v_writelane_b32 v253, s1, 14
	s_add_u32 s0, s88, 0x200
	s_addc_u32 s1, s89, 0
	v_writelane_b32 v253, s0, 15
	s_nop 1
	v_writelane_b32 v253, s1, 16
	s_add_u32 s0, s88, 0x1000
	s_addc_u32 s1, s89, 0
	v_writelane_b32 v253, s0, 17
	s_nop 1
	v_writelane_b32 v253, s1, 18
	s_add_u32 s0, s88, 0x1100
	s_addc_u32 s1, s89, 0
	v_writelane_b32 v253, s0, 19
	s_nop 1
	v_writelane_b32 v253, s1, 20
	s_add_u32 s0, s88, 0x1200
	s_addc_u32 s1, s89, 0
	v_writelane_b32 v253, s0, 21
	s_nop 1
	v_writelane_b32 v253, s1, 22
	s_add_u32 s0, s88, 0x1300
	s_addc_u32 s1, s89, 0
	v_writelane_b32 v253, s0, 23
	s_cmp_eq_u32 s20, 15
	s_nop 0
	v_writelane_b32 v253, s1, 24
	s_cselect_b64 s[0:1], -1, 0
	v_writelane_b32 v253, s0, 25
	s_cmp_eq_u32 s20, 14
	s_nop 0
	v_writelane_b32 v253, s1, 26
	s_cselect_b64 s[0:1], -1, 0
	v_writelane_b32 v253, s0, 27
	s_cmp_eq_u32 s20, 13
	s_nop 0
	v_writelane_b32 v253, s1, 28
	s_cselect_b64 s[0:1], -1, 0
	v_writelane_b32 v253, s0, 29
	s_cmp_eq_u32 s20, 12
	s_nop 0
	v_writelane_b32 v253, s1, 30
	s_cselect_b64 s[0:1], -1, 0
	v_writelane_b32 v253, s0, 31
	s_cmp_eq_u32 s20, 11
	s_nop 0
	v_writelane_b32 v253, s1, 32
	s_cselect_b64 s[0:1], -1, 0
	v_writelane_b32 v253, s0, 33
	s_cmp_eq_u32 s20, 10
	s_nop 0
	v_writelane_b32 v253, s1, 34
	s_cselect_b64 s[0:1], -1, 0
	v_writelane_b32 v253, s0, 35
	s_cmp_eq_u32 s20, 9
	s_nop 0
	v_writelane_b32 v253, s1, 36
	s_cselect_b64 s[0:1], -1, 0
	v_writelane_b32 v253, s0, 37
	s_cmp_eq_u32 s20, 8
	s_nop 0
	v_writelane_b32 v253, s1, 38
	s_cselect_b64 s[0:1], -1, 0
	v_writelane_b32 v253, s0, 39
	s_cmp_eq_u32 s20, 7
	s_nop 0
	v_writelane_b32 v253, s1, 40
	s_cselect_b64 s[0:1], -1, 0
	v_writelane_b32 v253, s0, 41
	s_cmp_eq_u32 s20, 6
	s_nop 0
	v_writelane_b32 v253, s1, 42
	s_cselect_b64 s[0:1], -1, 0
	v_writelane_b32 v253, s0, 43
	s_cmp_eq_u32 s20, 5
	s_nop 0
	v_writelane_b32 v253, s1, 44
	s_cselect_b64 s[0:1], -1, 0
	v_writelane_b32 v253, s0, 45
	s_cmp_eq_u32 s20, 4
	s_nop 0
	v_writelane_b32 v253, s1, 46
	s_cselect_b64 s[0:1], -1, 0
	v_writelane_b32 v253, s0, 47
	s_cmp_eq_u32 s20, 3
	s_nop 0
	v_writelane_b32 v253, s1, 48
	s_cselect_b64 s[0:1], -1, 0
	v_writelane_b32 v253, s0, 49
	s_cmp_eq_u32 s20, 2
	s_nop 0
	v_writelane_b32 v253, s1, 50
	s_cselect_b64 s[0:1], -1, 0
	v_writelane_b32 v253, s0, 51
	s_cmp_eq_u32 s20, 1
	s_nop 0
	v_writelane_b32 v253, s1, 52
	s_cselect_b64 s[0:1], -1, 0
	v_writelane_b32 v253, s0, 53
	s_cmp_eq_u32 s20, 0
	s_nop 0
	v_writelane_b32 v253, s1, 54
	s_cselect_b64 s[0:1], -1, 0
	v_writelane_b32 v253, s0, 55
	s_nop 1
	v_writelane_b32 v253, s1, 56
	s_lshl_b32 s0, s20, 8
	s_add_u32 s0, s88, s0
	s_addc_u32 s1, s89, 0
	s_add_u32 s2, s0, 0x1400
	s_addc_u32 s3, s1, 0
	v_writelane_b32 v253, s2, 57
	s_add_u32 s0, s0, 0x2400
	s_addc_u32 s1, s1, 0
	v_writelane_b32 v253, s3, 58
	v_writelane_b32 v253, s0, 59
	v_readlane_b32 s3, v252, 0
	s_nop 0
	v_writelane_b32 v253, s1, 60
	s_add_u32 s0, s88, 0x3400
	s_addc_u32 s1, s89, 0
	v_writelane_b32 v253, s0, 61
	s_nop 1
	v_writelane_b32 v253, s1, 62
	s_add_u32 s0, s88, 0x3500
	s_addc_u32 s1, s89, 0
	v_writelane_b32 v253, s0, 63
	s_cmp_lt_i32 s53, 0
	s_nop 0
	v_writelane_b32 v254, s1, 0
	s_cselect_b64 s[0:1], -1, 0
	v_writelane_b32 v254, s0, 1
	s_nop 1
	v_writelane_b32 v254, s1, 2
	s_movk_i32 s0, 0x3ff
	v_and_or_b32 v0, v0, s0, v194
	v_cmp_eq_u32_e64 s[0:1], 0, v0
	s_nop 1
	v_writelane_b32 v254, s0, 3
	s_nop 1
	v_writelane_b32 v254, s1, 4
	s_lshl_b32 s0, s3, 2
	v_writelane_b32 v254, s0, 5
	s_add_u32 s0, s42, 0x1000
	v_writelane_b32 v254, s36, 6
	s_addc_u32 s1, s43, 0
	s_cmp_lg_u64 s[84:85], 0
	v_writelane_b32 v254, s37, 7
	v_writelane_b32 v254, s38, 8
	v_writelane_b32 v254, s39, 9
	v_writelane_b32 v254, s40, 10
	v_writelane_b32 v254, s41, 11
	v_writelane_b32 v254, s42, 12
	v_writelane_b32 v254, s43, 13
	v_writelane_b32 v254, s44, 14
	v_writelane_b32 v254, s45, 15
	v_writelane_b32 v254, s46, 16
	v_writelane_b32 v254, s47, 17
	v_writelane_b32 v254, s48, 18
	v_writelane_b32 v254, s49, 19
	v_writelane_b32 v254, s50, 20
	v_writelane_b32 v254, s51, 21
	v_writelane_b32 v254, s0, 22
	s_mov_b64 s[36:37], 0x800
	s_nop 0
	v_writelane_b32 v254, s1, 23
	s_cselect_b64 s[0:1], -1, 0
	v_writelane_b32 v254, s0, 24
	s_cmpk_lt_i32 s3, 0x1560
	s_nop 0
	v_writelane_b32 v254, s1, 25
	s_cselect_b64 s[0:1], -1, 0
	v_writelane_b32 v254, s0, 26
	s_cmp_lg_u64 s[76:77], 0
	s_nop 0
	v_writelane_b32 v254, s1, 27
	s_cselect_b64 s[0:1], -1, 0
	v_writelane_b32 v254, s0, 28
	s_and_b32 s4, s3, 7
	s_lshl_b32 s2, s3, 4
	v_writelane_b32 v254, s1, 29
	s_lshr_b32 s0, s3, 3
	s_lshl_b32 s1, s4, 6
	v_writelane_b32 v254, s0, 30
	s_add_i32 s0, s1, s0
	v_writelane_b32 v254, s1, 31
	s_lshl_b32 s0, s0, 4
	s_and_b32 s2, s2, 0x380
	s_and_b32 s1, s0, 0xfffffc00
	v_writelane_b32 v254, s2, 32
	s_and_b32 s0, s0, 0x380
	v_writelane_b32 v254, s0, 33
	s_lshl_b32 s0, s3, 1
	s_and_b32 s0, s0, 0x7fffff80
	s_or_b32 s1, s1, s2
	s_addk_i32 s0, 0x4000
	v_writelane_b32 v254, s0, 34
	s_add_i32 s54, s1, 0x2000
	s_lshl_b32 s0, s4, 22
	v_writelane_b32 v254, s1, 35
	s_add_u32 s0, s80, s0
	v_writelane_b32 v254, s4, 36
	s_addc_u32 s1, s81, 0
	v_writelane_b32 v254, s0, 37
	s_nop 1
	v_writelane_b32 v254, s1, 38
	s_add_i32 s1, s22, -1
	s_mul_i32 s0, s1, 0x60
	v_writelane_b32 v254, s0, 39
	s_mul_i32 s0, s1, 0xa0
	v_writelane_b32 v254, s0, 40
	s_ashr_i32 s0, s1, 31
	v_writelane_b32 v254, s0, 41
	v_writelane_b32 v254, s22, 42
	s_sub_i32 s0, 1, s22
	s_max_i32 s0, s1, s0
	v_cvt_f32_u32_e32 v0, s0
	v_writelane_b32 v254, s23, 43
	v_writelane_b32 v254, s1, 44
	v_writelane_b32 v254, s0, 45
	v_rcp_iflag_f32_e32 v0, v0
	s_sub_i32 s0, 0, s0
	v_mul_f32_e32 v0, 0x4f7ffffe, v0
	v_cvt_u32_f32_e32 v0, v0
	s_nop 0
	v_readfirstlane_b32 s1, v0
	s_mul_i32 s0, s0, s1
	s_mul_hi_u32 s0, s1, s0
	s_add_i32 s0, s1, s0
	v_writelane_b32 v254, s0, 46
	s_add_u32 s0, s78, 64
	s_addc_u32 s1, s79, 0
	v_writelane_b32 v254, s0, 47
	v_mbcnt_lo_u32_b32 v0, -1, 0
	s_nop 0
	v_writelane_b32 v254, s1, 48
	v_readlane_b32 s0, v252, 1
	v_readlane_b32 s1, v252, 2
	s_add_u32 s2, s0, 0x100
	s_addc_u32 s3, s1, 0
	v_writelane_b32 v254, s2, 49
	v_mbcnt_hi_u32_b32 v202, -1, v0
	s_nop 0
	v_writelane_b32 v254, s3, 50
	s_add_u32 s2, s0, 0x140
	s_addc_u32 s3, s1, 0
	v_writelane_b32 v254, s2, 51
	s_nop 1
	v_writelane_b32 v254, s3, 52
	s_add_u32 s2, s0, 0x180
	s_addc_u32 s3, s1, 0
	v_writelane_b32 v254, s2, 53
	s_add_u32 s0, s0, 0x1c0
	s_addc_u32 s1, s1, 0
	v_writelane_b32 v254, s3, 54
	v_writelane_b32 v254, s0, 55
	s_mov_b32 s2, s52
	s_nop 0
	v_writelane_b32 v254, s1, 56
	s_add_u32 s0, s78, 0x2c00
	s_addc_u32 s1, s79, 0
	v_writelane_b32 v254, s0, 57
	s_nop 1
	v_writelane_b32 v254, s1, 58
	v_writelane_b32 v254, s54, 59
	v_writelane_b32 v254, s52, 60
	s_nop 1
	v_writelane_b32 v254, s53, 61
	s_branch .LBB0_9

.Lpc_prod_5:
.Lpc_ptop_5:
	s_mov_b32 s30, s52
	s_cmp_lt_i32 s53, s52
	s_cbranch_scc1 .Lpc_pcur_5
	s_mov_b32 vcc_lo, 0
	s_cmp_lg_u64 s[22:23], 0
	s_cbranch_scc1 .Lpc_pnext_5
	v_readfirstlane_b32 s26, v150
	v_readfirstlane_b32 s27, v151
	v_readfirstlane_b32 s38, v148
	v_readfirstlane_b32 s39, v149
	s_branch .Lpc_pgo_5
.Lpc_pnext_5:
	s_mov_b32 s30, s43
	v_readfirstlane_b32 s26, v0
	v_readfirstlane_b32 s27, v1
	v_readfirstlane_b32 s38, v138
	v_readfirstlane_b32 s39, v139
	s_branch .Lpc_pgo_5

.Lpc_pgo_5:
	s_nop 0
	s_sub_u32 s26, s26, s98
	s_subb_u32 s27, s27, 0
	s_sub_u32 s38, s38, s99
	s_subb_u32 s39, s39, 0
	s_mov_b32 vcc_hi, vcc_lo
	s_add_u32 m0, s30, -1
	s_and_b32 vcc_hi, vcc_hi, m0
	s_lshl_b32 vcc_hi, vcc_hi, 7
	v_add_u32_e32 v20, vcc_hi, v4
	v_add_u32_e32 v21, vcc_hi, v5
	v_add_u32_e32 v22, vcc_hi, v6
	v_add_u32_e32 v23, vcc_hi, v7
	v_add_u32_e32 v24, vcc_hi, v8
	v_add_u32_e32 v25, vcc_hi, v9
	v_add_u32_e32 v26, vcc_hi, v10
	v_add_u32_e32 v27, vcc_hi, v11
	v_add_u32_e32 v28, vcc_hi, v12
	v_add_u32_e32 v29, vcc_hi, v13
	v_add_u32_e32 v30, vcc_hi, v14
	v_add_u32_e32 v31, vcc_hi, v15
	v_add_u32_e32 v32, vcc_hi, v16
	v_add_u32_e32 v33, vcc_hi, v17
	v_add_u32_e32 v34, vcc_hi, v18
	v_add_u32_e32 v35, vcc_hi, v19
	s_add_u32 vcc_lo, vcc_lo, 1
	s_barrier
	s_add_u32 m0, s100, 0x0
	s_nop 0
	global_load_lds_dwordx4 v20, s[26:27]
	s_add_u32 m0, s100, 0x400
	s_nop 0
	global_load_lds_dwordx4 v21, s[26:27]
	s_add_u32 m0, s100, 0x1000
	s_nop 0
	global_load_lds_dwordx4 v22, s[26:27]
	s_add_u32 m0, s100, 0x1400
	s_nop 0
	global_load_lds_dwordx4 v23, s[26:27]
	s_add_u32 m0, s100, 0x2000
	s_nop 0
	global_load_lds_dwordx4 v24, s[26:27]
	s_add_u32 m0, s100, 0x2400
	s_nop 0
	global_load_lds_dwordx4 v25, s[26:27]
	s_add_u32 m0, s100, 0x3000
	s_nop 0
	global_load_lds_dwordx4 v26, s[26:27]
	s_add_u32 m0, s100, 0x3400
	s_nop 0
	global_load_lds_dwordx4 v27, s[26:27]
	s_waitcnt vmcnt(8)
	s_barrier
	s_add_u32 m0, s100, 0x4000
	s_nop 0
	global_load_lds_dwordx4 v28, s[38:39]
	s_add_u32 m0, s100, 0x4400
	s_nop 0
	global_load_lds_dwordx4 v29, s[38:39]
	s_add_u32 m0, s100, 0x5000
	s_nop 0
	global_load_lds_dwordx4 v30, s[38:39]
	s_add_u32 m0, s100, 0x5400
	s_nop 0
	global_load_lds_dwordx4 v31, s[38:39]
	s_add_u32 m0, s100, 0x6000
	s_nop 0
	global_load_lds_dwordx4 v32, s[38:39]
	s_add_u32 m0, s100, 0x6400
	s_nop 0
	global_load_lds_dwordx4 v33, s[38:39]
	s_add_u32 m0, s100, 0x7000
	s_nop 0
	global_load_lds_dwordx4 v34, s[38:39]
	s_add_u32 m0, s100, 0x7400
	s_nop 0
	global_load_lds_dwordx4 v35, s[38:39]
	s_mov_b32 vcc_hi, vcc_lo
	s_add_u32 m0, s30, -1
	s_and_b32 vcc_hi, vcc_hi, m0
	s_lshl_b32 vcc_hi, vcc_hi, 7
	v_add_u32_e32 v20, vcc_hi, v4
	v_add_u32_e32 v21, vcc_hi, v5
	v_add_u32_e32 v22, vcc_hi, v6
	v_add_u32_e32 v23, vcc_hi, v7
	v_add_u32_e32 v24, vcc_hi, v8
	v_add_u32_e32 v25, vcc_hi, v9
	v_add_u32_e32 v26, vcc_hi, v10
	v_add_u32_e32 v27, vcc_hi, v11
	v_add_u32_e32 v28, vcc_hi, v12
	v_add_u32_e32 v29, vcc_hi, v13
	v_add_u32_e32 v30, vcc_hi, v14
	v_add_u32_e32 v31, vcc_hi, v15
	v_add_u32_e32 v32, vcc_hi, v16
	v_add_u32_e32 v33, vcc_hi, v17
	v_add_u32_e32 v34, vcc_hi, v18
	v_add_u32_e32 v35, vcc_hi, v19
	s_add_u32 vcc_lo, vcc_lo, 1
	s_barrier
	s_add_u32 m0, s100, 0x8000
	s_nop 0
	global_load_lds_dwordx4 v20, s[26:27]
	s_add_u32 m0, s100, 0x8400
	s_nop 0
	global_load_lds_dwordx4 v21, s[26:27]
	s_add_u32 m0, s100, 0x9000
	s_nop 0
	global_load_lds_dwordx4 v22, s[26:27]
	s_add_u32 m0, s100, 0x9400
	s_nop 0
	global_load_lds_dwordx4 v23, s[26:27]
	s_add_u32 m0, s100, 0xa000
	s_nop 0
	global_load_lds_dwordx4 v24, s[26:27]
	s_add_u32 m0, s100, 0xa400
	s_nop 0
	global_load_lds_dwordx4 v25, s[26:27]
	s_add_u32 m0, s100, 0xb000
	s_nop 0
	global_load_lds_dwordx4 v26, s[26:27]
	s_add_u32 m0, s100, 0xb400
	s_nop 0
	global_load_lds_dwordx4 v27, s[26:27]
	s_waitcnt vmcnt(8)
	s_barrier
	s_add_u32 m0, s100, 0xc000
	s_nop 0
	global_load_lds_dwordx4 v28, s[38:39]
	s_add_u32 m0, s100, 0xc400
	s_nop 0
	global_load_lds_dwordx4 v29, s[38:39]
	s_add_u32 m0, s100, 0xd000
	s_nop 0
	global_load_lds_dwordx4 v30, s[38:39]
	s_add_u32 m0, s100, 0xd400
	s_nop 0
	global_load_lds_dwordx4 v31, s[38:39]
	s_add_u32 m0, s100, 0xe000
	s_nop 0
	global_load_lds_dwordx4 v32, s[38:39]
	s_add_u32 m0, s100, 0xe400
	s_nop 0
	global_load_lds_dwordx4 v33, s[38:39]
	s_add_u32 m0, s100, 0xf000
	s_nop 0
	global_load_lds_dwordx4 v34, s[38:39]
	s_add_u32 m0, s100, 0xf400
	s_nop 0
	global_load_lds_dwordx4 v35, s[38:39]
	s_add_u32 s24, s24, 0x100
	s_addc_u32 s25, s25, 0
	s_add_i32 s53, s53, 2
	s_cmp_le_i32 s53, s52
	s_cbranch_scc1 .Lpc_ptop_5
	s_add_i32 s42, s42, 1
	s_mov_b32 s46, s44
	s_mov_b32 s47, s45
	s_cmp_eq_u32 s42, 3
	s_cbranch_scc0 .Lpc_pnd_5
	s_waitcnt vmcnt(0)
	s_branch .LBB0_165

.Lpc_prod_2:
.Lpc_ptop_2:
	s_mov_b32 s42, s47
	s_cmp_lt_i32 s55, s47
	s_cbranch_scc1 .Lpc_pcur_2
	s_mov_b32 vcc_lo, 0
	s_cmp_lg_u64 s[30:31], 0
	s_cbranch_scc1 .Lpc_pnext_2
	v_readfirstlane_b32 s40, v144
	v_readfirstlane_b32 s41, v145
	v_readfirstlane_b32 s38, v146
	v_readfirstlane_b32 s39, v147
	s_branch .Lpc_pgo_2

.Lpc_pgo_2:
	s_nop 0
	s_sub_u32 s40, s40, s98
	s_subb_u32 s41, s41, 0
	s_sub_u32 s38, s38, s99
	s_subb_u32 s39, s39, 0
	s_bfe_u32 vcc_hi, s101, 0x80008
	s_add_u32 vcc_hi, vcc_hi, vcc_lo
	s_add_u32 m0, s42, -1
	s_and_b32 vcc_hi, vcc_hi, m0
	s_lshl_b32 vcc_hi, vcc_hi, 7
	v_add_u32_e32 v20, vcc_hi, v4
	v_add_u32_e32 v21, vcc_hi, v5
	v_add_u32_e32 v22, vcc_hi, v6
	v_add_u32_e32 v23, vcc_hi, v7
	v_add_u32_e32 v24, vcc_hi, v8
	v_add_u32_e32 v25, vcc_hi, v9
	v_add_u32_e32 v26, vcc_hi, v10
	v_add_u32_e32 v27, vcc_hi, v11
	v_add_u32_e32 v28, vcc_hi, v12
	v_add_u32_e32 v29, vcc_hi, v13
	v_add_u32_e32 v30, vcc_hi, v14
	v_add_u32_e32 v31, vcc_hi, v15
	v_add_u32_e32 v32, vcc_hi, v16
	v_add_u32_e32 v33, vcc_hi, v17
	v_add_u32_e32 v34, vcc_hi, v18
	v_add_u32_e32 v35, vcc_hi, v19
	s_add_u32 vcc_lo, vcc_lo, 1
	s_barrier
	s_add_u32 m0, s100, 0x0
	s_nop 0
	global_load_lds_dwordx4 v20, s[40:41]
	s_add_u32 m0, s100, 0x400
	s_nop 0
	global_load_lds_dwordx4 v21, s[40:41]
	s_add_u32 m0, s100, 0x1000
	s_nop 0
	global_load_lds_dwordx4 v22, s[40:41]
	s_add_u32 m0, s100, 0x1400
	s_nop 0
	global_load_lds_dwordx4 v23, s[40:41]
	s_add_u32 m0, s100, 0x2000
	s_nop 0
	global_load_lds_dwordx4 v24, s[40:41]
	s_add_u32 m0, s100, 0x2400
	s_nop 0
	global_load_lds_dwordx4 v25, s[40:41]
	s_add_u32 m0, s100, 0x3000
	s_nop 0
	global_load_lds_dwordx4 v26, s[40:41]
	s_add_u32 m0, s100, 0x3400
	s_nop 0
	global_load_lds_dwordx4 v27, s[40:41]
	s_waitcnt vmcnt(8)
	s_barrier
	s_add_u32 m0, s100, 0x4000
	s_nop 0
	global_load_lds_dwordx4 v28, s[38:39]
	s_add_u32 m0, s100, 0x4400
	s_nop 0
	global_load_lds_dwordx4 v29, s[38:39]
	s_add_u32 m0, s100, 0x5000
	s_nop 0
	global_load_lds_dwordx4 v30, s[38:39]
	s_add_u32 m0, s100, 0x5400
	s_nop 0
	global_load_lds_dwordx4 v31, s[38:39]
	s_add_u32 m0, s100, 0x6000
	s_nop 0
	global_load_lds_dwordx4 v32, s[38:39]
	s_add_u32 m0, s100, 0x6400
	s_nop 0
	global_load_lds_dwordx4 v33, s[38:39]
	s_add_u32 m0, s100, 0x7000
	s_nop 0
	global_load_lds_dwordx4 v34, s[38:39]
	s_add_u32 m0, s100, 0x7400
	s_nop 0
	global_load_lds_dwordx4 v35, s[38:39]
	s_bfe_u32 vcc_hi, s101, 0x80008
	s_add_u32 vcc_hi, vcc_hi, vcc_lo
	s_add_u32 m0, s42, -1
	s_and_b32 vcc_hi, vcc_hi, m0
	s_lshl_b32 vcc_hi, vcc_hi, 7
	v_add_u32_e32 v20, vcc_hi, v4
	v_add_u32_e32 v21, vcc_hi, v5
	v_add_u32_e32 v22, vcc_hi, v6
	v_add_u32_e32 v23, vcc_hi, v7
	v_add_u32_e32 v24, vcc_hi, v8
	v_add_u32_e32 v25, vcc_hi, v9
	v_add_u32_e32 v26, vcc_hi, v10
	v_add_u32_e32 v27, vcc_hi, v11
	v_add_u32_e32 v28, vcc_hi, v12
	v_add_u32_e32 v29, vcc_hi, v13
	v_add_u32_e32 v30, vcc_hi, v14
	v_add_u32_e32 v31, vcc_hi, v15
	v_add_u32_e32 v32, vcc_hi, v16
	v_add_u32_e32 v33, vcc_hi, v17
	v_add_u32_e32 v34, vcc_hi, v18
	v_add_u32_e32 v35, vcc_hi, v19
	s_add_u32 vcc_lo, vcc_lo, 1
	s_barrier
	s_add_u32 m0, s100, 0x8000
	s_nop 0
	global_load_lds_dwordx4 v20, s[40:41]
	s_add_u32 m0, s100, 0x8400
	s_nop 0
	global_load_lds_dwordx4 v21, s[40:41]
	s_add_u32 m0, s100, 0x9000
	s_nop 0
	global_load_lds_dwordx4 v22, s[40:41]
	s_add_u32 m0, s100, 0x9400
	s_nop 0
	global_load_lds_dwordx4 v23, s[40:41]
	s_add_u32 m0, s100, 0xa000
	s_nop 0
	global_load_lds_dwordx4 v24, s[40:41]
	s_add_u32 m0, s100, 0xa400
	s_nop 0
	global_load_lds_dwordx4 v25, s[40:41]
	s_add_u32 m0, s100, 0xb000
	s_nop 0
	global_load_lds_dwordx4 v26, s[40:41]
	s_add_u32 m0, s100, 0xb400
	s_nop 0
	global_load_lds_dwordx4 v27, s[40:41]
	s_waitcnt vmcnt(8)
	s_barrier
	s_add_u32 m0, s100, 0xc000
	s_nop 0
	global_load_lds_dwordx4 v28, s[38:39]
	s_add_u32 m0, s100, 0xc400
	s_nop 0
	global_load_lds_dwordx4 v29, s[38:39]
	s_add_u32 m0, s100, 0xd000
	s_nop 0
	global_load_lds_dwordx4 v30, s[38:39]
	s_add_u32 m0, s100, 0xd400
	s_nop 0
	global_load_lds_dwordx4 v31, s[38:39]
	s_add_u32 m0, s100, 0xe000
	s_nop 0
	global_load_lds_dwordx4 v32, s[38:39]
	s_add_u32 m0, s100, 0xe400
	s_nop 0
	global_load_lds_dwordx4 v33, s[38:39]
	s_add_u32 m0, s100, 0xf000
	s_nop 0
	global_load_lds_dwordx4 v34, s[38:39]
	s_add_u32 m0, s100, 0xf400
	s_nop 0
	global_load_lds_dwordx4 v35, s[38:39]
	s_add_u32 s34, s34, 0x100
	s_addc_u32 s35, s35, 0
	s_add_i32 s55, s55, 2
	s_cmp_le_i32 s55, s47
	s_cbranch_scc1 .Lpc_ptop_2
	s_movk_i32 s55, 0x4000
	s_mov_b32 s53, s1
	s_mov_b32 s52, s3
	s_and_b64 vcc, exec, s[26:27]
	v_mov_b64_e32 v[146:147], v[142:143]
	v_mov_b64_e32 v[144:145], v[140:141]
	s_cbranch_vccz .Lpc_pnd_2
	s_waitcnt vmcnt(0)
	s_branch .LBB0_191

.Lpc_prod_6:
.Lpc_ptop_6:
	s_mov_b32 s30, s49
	s_cmp_lt_i32 s52, s49
	s_cbranch_scc1 .Lpc_pcur_6
	s_mov_b32 vcc_lo, 0
	s_cmp_lg_u64 s[22:23], 0
	s_cbranch_scc1 .Lpc_pnext_6
	v_readfirstlane_b32 s26, v150
	v_readfirstlane_b32 s27, v151
	v_readfirstlane_b32 s38, v148
	v_readfirstlane_b32 s39, v149
	s_branch .Lpc_pgo_6

.Lpc_pgo_6:
	s_nop 0
	s_sub_u32 s26, s26, s98
	s_subb_u32 s27, s27, 0
	s_sub_u32 s38, s38, s99
	s_subb_u32 s39, s39, 0
	s_mov_b32 vcc_hi, vcc_lo
	s_add_u32 m0, s30, -1
	s_and_b32 vcc_hi, vcc_hi, m0
	s_lshl_b32 vcc_hi, vcc_hi, 7
	v_add_u32_e32 v20, vcc_hi, v4
	v_add_u32_e32 v21, vcc_hi, v5
	v_add_u32_e32 v22, vcc_hi, v6
	v_add_u32_e32 v23, vcc_hi, v7
	v_add_u32_e32 v24, vcc_hi, v8
	v_add_u32_e32 v25, vcc_hi, v9
	v_add_u32_e32 v26, vcc_hi, v10
	v_add_u32_e32 v27, vcc_hi, v11
	v_add_u32_e32 v28, vcc_hi, v12
	v_add_u32_e32 v29, vcc_hi, v13
	v_add_u32_e32 v30, vcc_hi, v14
	v_add_u32_e32 v31, vcc_hi, v15
	v_add_u32_e32 v32, vcc_hi, v16
	v_add_u32_e32 v33, vcc_hi, v17
	v_add_u32_e32 v34, vcc_hi, v18
	v_add_u32_e32 v35, vcc_hi, v19
	s_add_u32 vcc_lo, vcc_lo, 1
	s_barrier
	s_add_u32 m0, s100, 0x0
	s_nop 0
	global_load_lds_dwordx4 v20, s[26:27]
	s_add_u32 m0, s100, 0x400
	s_nop 0
	global_load_lds_dwordx4 v21, s[26:27]
	s_add_u32 m0, s100, 0x1000
	s_nop 0
	global_load_lds_dwordx4 v22, s[26:27]
	s_add_u32 m0, s100, 0x1400
	s_nop 0
	global_load_lds_dwordx4 v23, s[26:27]
	s_add_u32 m0, s100, 0x2000
	s_nop 0
	global_load_lds_dwordx4 v24, s[26:27]
	s_add_u32 m0, s100, 0x2400
	s_nop 0
	global_load_lds_dwordx4 v25, s[26:27]
	s_add_u32 m0, s100, 0x3000
	s_nop 0
	global_load_lds_dwordx4 v26, s[26:27]
	s_add_u32 m0, s100, 0x3400
	s_nop 0
	global_load_lds_dwordx4 v27, s[26:27]
	s_waitcnt vmcnt(8)
	s_barrier
	s_add_u32 m0, s100, 0x4000
	s_nop 0
	global_load_lds_dwordx4 v28, s[38:39]
	s_add_u32 m0, s100, 0x4400
	s_nop 0
	global_load_lds_dwordx4 v29, s[38:39]
	s_add_u32 m0, s100, 0x5000
	s_nop 0
	global_load_lds_dwordx4 v30, s[38:39]
	s_add_u32 m0, s100, 0x5400
	s_nop 0
	global_load_lds_dwordx4 v31, s[38:39]
	s_add_u32 m0, s100, 0x6000
	s_nop 0
	global_load_lds_dwordx4 v32, s[38:39]
	s_add_u32 m0, s100, 0x6400
	s_nop 0
	global_load_lds_dwordx4 v33, s[38:39]
	s_add_u32 m0, s100, 0x7000
	s_nop 0
	global_load_lds_dwordx4 v34, s[38:39]
	s_add_u32 m0, s100, 0x7400
	s_nop 0
	global_load_lds_dwordx4 v35, s[38:39]
	s_mov_b32 vcc_hi, vcc_lo
	s_add_u32 m0, s30, -1
	s_and_b32 vcc_hi, vcc_hi, m0
	s_lshl_b32 vcc_hi, vcc_hi, 7
	v_add_u32_e32 v20, vcc_hi, v4
	v_add_u32_e32 v21, vcc_hi, v5
	v_add_u32_e32 v22, vcc_hi, v6
	v_add_u32_e32 v23, vcc_hi, v7
	v_add_u32_e32 v24, vcc_hi, v8
	v_add_u32_e32 v25, vcc_hi, v9
	v_add_u32_e32 v26, vcc_hi, v10
	v_add_u32_e32 v27, vcc_hi, v11
	v_add_u32_e32 v28, vcc_hi, v12
	v_add_u32_e32 v29, vcc_hi, v13
	v_add_u32_e32 v30, vcc_hi, v14
	v_add_u32_e32 v31, vcc_hi, v15
	v_add_u32_e32 v32, vcc_hi, v16
	v_add_u32_e32 v33, vcc_hi, v17
	v_add_u32_e32 v34, vcc_hi, v18
	v_add_u32_e32 v35, vcc_hi, v19
	s_add_u32 vcc_lo, vcc_lo, 1
	s_barrier
	s_add_u32 m0, s100, 0x8000
	s_nop 0
	global_load_lds_dwordx4 v20, s[26:27]
	s_add_u32 m0, s100, 0x8400
	s_nop 0
	global_load_lds_dwordx4 v21, s[26:27]
	s_add_u32 m0, s100, 0x9000
	s_nop 0
	global_load_lds_dwordx4 v22, s[26:27]
	s_add_u32 m0, s100, 0x9400
	s_nop 0
	global_load_lds_dwordx4 v23, s[26:27]
	s_add_u32 m0, s100, 0xa000
	s_nop 0
	global_load_lds_dwordx4 v24, s[26:27]
	s_add_u32 m0, s100, 0xa400
	s_nop 0
	global_load_lds_dwordx4 v25, s[26:27]
	s_add_u32 m0, s100, 0xb000
	s_nop 0
	global_load_lds_dwordx4 v26, s[26:27]
	s_add_u32 m0, s100, 0xb400
	s_nop 0
	global_load_lds_dwordx4 v27, s[26:27]
	s_waitcnt vmcnt(8)
	s_barrier
	s_add_u32 m0, s100, 0xc000
	s_nop 0
	global_load_lds_dwordx4 v28, s[38:39]
	s_add_u32 m0, s100, 0xc400
	s_nop 0
	global_load_lds_dwordx4 v29, s[38:39]
	s_add_u32 m0, s100, 0xd000
	s_nop 0
	global_load_lds_dwordx4 v30, s[38:39]
	s_add_u32 m0, s100, 0xd400
	s_nop 0
	global_load_lds_dwordx4 v31, s[38:39]
	s_add_u32 m0, s100, 0xe000
	s_nop 0
	global_load_lds_dwordx4 v32, s[38:39]
	s_add_u32 m0, s100, 0xe400
	s_nop 0
	global_load_lds_dwordx4 v33, s[38:39]
	s_add_u32 m0, s100, 0xf000
	s_nop 0
	global_load_lds_dwordx4 v34, s[38:39]
	s_add_u32 m0, s100, 0xf400
	s_nop 0
	global_load_lds_dwordx4 v35, s[38:39]
	s_add_u32 s24, s24, 0x100
	s_addc_u32 s25, s25, 0
	s_add_i32 s52, s52, 2
	s_cmp_le_i32 s52, s49
	s_cbranch_scc1 .Lpc_ptop_6
	s_add_i32 s42, s42, 1
	s_mov_b32 s46, s44
	s_mov_b32 s47, s45
	s_cmp_eq_u32 s42, 3
	s_cbranch_scc0 .Lpc_pnd_6
	s_waitcnt vmcnt(0)
	s_branch .LBB0_276

.Lpc_prod_3:
.Lpc_ptop_3:
	s_mov_b32 s42, s47
	s_cmp_lt_i32 s96, s47
	s_cbranch_scc1 .Lpc_pcur_3
	s_mov_b32 vcc_lo, 0
	s_cmp_lg_u64 s[30:31], 0
	s_cbranch_scc1 .Lpc_pnext_3
	v_readfirstlane_b32 s40, v144
	v_readfirstlane_b32 s41, v145
	v_readfirstlane_b32 s38, v146
	v_readfirstlane_b32 s39, v147
	s_branch .Lpc_pgo_3

.Lpc_pgo_3:
	s_nop 0
	s_sub_u32 s40, s40, s98
	s_subb_u32 s41, s41, 0
	s_sub_u32 s38, s38, s99
	s_subb_u32 s39, s39, 0
	s_bfe_u32 vcc_hi, s101, 0x80008
	s_add_u32 vcc_hi, vcc_hi, vcc_lo
	s_add_u32 m0, s42, -1
	s_and_b32 vcc_hi, vcc_hi, m0
	s_lshl_b32 vcc_hi, vcc_hi, 7
	v_add_u32_e32 v20, vcc_hi, v4
	v_add_u32_e32 v21, vcc_hi, v5
	v_add_u32_e32 v22, vcc_hi, v6
	v_add_u32_e32 v23, vcc_hi, v7
	v_add_u32_e32 v24, vcc_hi, v8
	v_add_u32_e32 v25, vcc_hi, v9
	v_add_u32_e32 v26, vcc_hi, v10
	v_add_u32_e32 v27, vcc_hi, v11
	v_add_u32_e32 v28, vcc_hi, v12
	v_add_u32_e32 v29, vcc_hi, v13
	v_add_u32_e32 v30, vcc_hi, v14
	v_add_u32_e32 v31, vcc_hi, v15
	v_add_u32_e32 v32, vcc_hi, v16
	v_add_u32_e32 v33, vcc_hi, v17
	v_add_u32_e32 v34, vcc_hi, v18
	v_add_u32_e32 v35, vcc_hi, v19
	s_add_u32 vcc_lo, vcc_lo, 1
	s_barrier
	s_add_u32 m0, s100, 0x0
	s_nop 0
	global_load_lds_dwordx4 v20, s[40:41]
	s_add_u32 m0, s100, 0x400
	s_nop 0
	global_load_lds_dwordx4 v21, s[40:41]
	s_add_u32 m0, s100, 0x1000
	s_nop 0
	global_load_lds_dwordx4 v22, s[40:41]
	s_add_u32 m0, s100, 0x1400
	s_nop 0
	global_load_lds_dwordx4 v23, s[40:41]
	s_add_u32 m0, s100, 0x2000
	s_nop 0
	global_load_lds_dwordx4 v24, s[40:41]
	s_add_u32 m0, s100, 0x2400
	s_nop 0
	global_load_lds_dwordx4 v25, s[40:41]
	s_add_u32 m0, s100, 0x3000
	s_nop 0
	global_load_lds_dwordx4 v26, s[40:41]
	s_add_u32 m0, s100, 0x3400
	s_nop 0
	global_load_lds_dwordx4 v27, s[40:41]
	s_waitcnt vmcnt(8)
	s_barrier
	s_add_u32 m0, s100, 0x4000
	s_nop 0
	global_load_lds_dwordx4 v28, s[38:39]
	s_add_u32 m0, s100, 0x4400
	s_nop 0
	global_load_lds_dwordx4 v29, s[38:39]
	s_add_u32 m0, s100, 0x5000
	s_nop 0
	global_load_lds_dwordx4 v30, s[38:39]
	s_add_u32 m0, s100, 0x5400
	s_nop 0
	global_load_lds_dwordx4 v31, s[38:39]
	s_add_u32 m0, s100, 0x6000
	s_nop 0
	global_load_lds_dwordx4 v32, s[38:39]
	s_add_u32 m0, s100, 0x6400
	s_nop 0
	global_load_lds_dwordx4 v33, s[38:39]
	s_add_u32 m0, s100, 0x7000
	s_nop 0
	global_load_lds_dwordx4 v34, s[38:39]
	s_add_u32 m0, s100, 0x7400
	s_nop 0
	global_load_lds_dwordx4 v35, s[38:39]
	s_bfe_u32 vcc_hi, s101, 0x80008
	s_add_u32 vcc_hi, vcc_hi, vcc_lo
	s_add_u32 m0, s42, -1
	s_and_b32 vcc_hi, vcc_hi, m0
	s_lshl_b32 vcc_hi, vcc_hi, 7
	v_add_u32_e32 v20, vcc_hi, v4
	v_add_u32_e32 v21, vcc_hi, v5
	v_add_u32_e32 v22, vcc_hi, v6
	v_add_u32_e32 v23, vcc_hi, v7
	v_add_u32_e32 v24, vcc_hi, v8
	v_add_u32_e32 v25, vcc_hi, v9
	v_add_u32_e32 v26, vcc_hi, v10
	v_add_u32_e32 v27, vcc_hi, v11
	v_add_u32_e32 v28, vcc_hi, v12
	v_add_u32_e32 v29, vcc_hi, v13
	v_add_u32_e32 v30, vcc_hi, v14
	v_add_u32_e32 v31, vcc_hi, v15
	v_add_u32_e32 v32, vcc_hi, v16
	v_add_u32_e32 v33, vcc_hi, v17
	v_add_u32_e32 v34, vcc_hi, v18
	v_add_u32_e32 v35, vcc_hi, v19
	s_add_u32 vcc_lo, vcc_lo, 1
	s_barrier
	s_add_u32 m0, s100, 0x8000
	s_nop 0
	global_load_lds_dwordx4 v20, s[40:41]
	s_add_u32 m0, s100, 0x8400
	s_nop 0
	global_load_lds_dwordx4 v21, s[40:41]
	s_add_u32 m0, s100, 0x9000
	s_nop 0
	global_load_lds_dwordx4 v22, s[40:41]
	s_add_u32 m0, s100, 0x9400
	s_nop 0
	global_load_lds_dwordx4 v23, s[40:41]
	s_add_u32 m0, s100, 0xa000
	s_nop 0
	global_load_lds_dwordx4 v24, s[40:41]
	s_add_u32 m0, s100, 0xa400
	s_nop 0
	global_load_lds_dwordx4 v25, s[40:41]
	s_add_u32 m0, s100, 0xb000
	s_nop 0
	global_load_lds_dwordx4 v26, s[40:41]
	s_add_u32 m0, s100, 0xb400
	s_nop 0
	global_load_lds_dwordx4 v27, s[40:41]
	s_waitcnt vmcnt(8)
	s_barrier
	s_add_u32 m0, s100, 0xc000
	s_nop 0
	global_load_lds_dwordx4 v28, s[38:39]
	s_add_u32 m0, s100, 0xc400
	s_nop 0
	global_load_lds_dwordx4 v29, s[38:39]
	s_add_u32 m0, s100, 0xd000
	s_nop 0
	global_load_lds_dwordx4 v30, s[38:39]
	s_add_u32 m0, s100, 0xd400
	s_nop 0
	global_load_lds_dwordx4 v31, s[38:39]
	s_add_u32 m0, s100, 0xe000
	s_nop 0
	global_load_lds_dwordx4 v32, s[38:39]
	s_add_u32 m0, s100, 0xe400
	s_nop 0
	global_load_lds_dwordx4 v33, s[38:39]
	s_add_u32 m0, s100, 0xf000
	s_nop 0
	global_load_lds_dwordx4 v34, s[38:39]
	s_add_u32 m0, s100, 0xf400
	s_nop 0
	global_load_lds_dwordx4 v35, s[38:39]
	s_add_u32 s34, s34, 0x100
	s_addc_u32 s35, s35, 0
	s_add_i32 s96, s96, 2
	s_cmp_le_i32 s96, s47
	s_cbranch_scc1 .Lpc_ptop_3
	s_mov_b32 s97, s5
	s_movk_i32 s96, 0x43ff
	s_mov_b32 s55, s49
	s_mov_b32 s53, s1
	s_and_b64 vcc, exec, s[26:27]
	v_mov_b64_e32 v[146:147], v[142:143]
	v_mov_b64_e32 v[144:145], v[140:141]
	s_cbranch_vccz .Lpc_pnd_3
	s_waitcnt vmcnt(0)
	s_branch .LBB0_319

.Lpc_pgo_4:
	s_nop 0
	s_sub_u32 s40, s40, s98
	s_subb_u32 s41, s41, 0
	s_sub_u32 s38, s38, s99
	s_subb_u32 s39, s39, 0
	s_bfe_u32 vcc_hi, s101, 0x80008
	s_add_u32 vcc_hi, vcc_hi, vcc_lo
	s_add_u32 m0, s42, -1
	s_and_b32 vcc_hi, vcc_hi, m0
	s_lshl_b32 vcc_hi, vcc_hi, 7
	v_add_u32_e32 v20, vcc_hi, v4
	v_add_u32_e32 v21, vcc_hi, v5
	v_add_u32_e32 v22, vcc_hi, v6
	v_add_u32_e32 v23, vcc_hi, v7
	v_add_u32_e32 v24, vcc_hi, v8
	v_add_u32_e32 v25, vcc_hi, v9
	v_add_u32_e32 v26, vcc_hi, v10
	v_add_u32_e32 v27, vcc_hi, v11
	v_add_u32_e32 v28, vcc_hi, v12
	v_add_u32_e32 v29, vcc_hi, v13
	v_add_u32_e32 v30, vcc_hi, v14
	v_add_u32_e32 v31, vcc_hi, v15
	v_add_u32_e32 v32, vcc_hi, v16
	v_add_u32_e32 v33, vcc_hi, v17
	v_add_u32_e32 v34, vcc_hi, v18
	v_add_u32_e32 v35, vcc_hi, v19
	s_add_u32 vcc_lo, vcc_lo, 1
	s_barrier
	s_add_u32 m0, s100, 0x0
	s_nop 0
	global_load_lds_dwordx4 v20, s[40:41]
	s_add_u32 m0, s100, 0x400
	s_nop 0
	global_load_lds_dwordx4 v21, s[40:41]
	s_add_u32 m0, s100, 0x1000
	s_nop 0
	global_load_lds_dwordx4 v22, s[40:41]
	s_add_u32 m0, s100, 0x1400
	s_nop 0
	global_load_lds_dwordx4 v23, s[40:41]
	s_add_u32 m0, s100, 0x2000
	s_nop 0
	global_load_lds_dwordx4 v24, s[40:41]
	s_add_u32 m0, s100, 0x2400
	s_nop 0
	global_load_lds_dwordx4 v25, s[40:41]
	s_add_u32 m0, s100, 0x3000
	s_nop 0
	global_load_lds_dwordx4 v26, s[40:41]
	s_add_u32 m0, s100, 0x3400
	s_nop 0
	global_load_lds_dwordx4 v27, s[40:41]
	s_waitcnt vmcnt(8)
	s_barrier
	s_add_u32 m0, s100, 0x4000
	s_nop 0
	global_load_lds_dwordx4 v28, s[38:39]
	s_add_u32 m0, s100, 0x4400
	s_nop 0
	global_load_lds_dwordx4 v29, s[38:39]
	s_add_u32 m0, s100, 0x5000
	s_nop 0
	global_load_lds_dwordx4 v30, s[38:39]
	s_add_u32 m0, s100, 0x5400
	s_nop 0
	global_load_lds_dwordx4 v31, s[38:39]
	s_add_u32 m0, s100, 0x6000
	s_nop 0
	global_load_lds_dwordx4 v32, s[38:39]
	s_add_u32 m0, s100, 0x6400
	s_nop 0
	global_load_lds_dwordx4 v33, s[38:39]
	s_add_u32 m0, s100, 0x7000
	s_nop 0
	global_load_lds_dwordx4 v34, s[38:39]
	s_add_u32 m0, s100, 0x7400
	s_nop 0
	global_load_lds_dwordx4 v35, s[38:39]
	s_bfe_u32 vcc_hi, s101, 0x80008
	s_add_u32 vcc_hi, vcc_hi, vcc_lo
	s_add_u32 m0, s42, -1
	s_and_b32 vcc_hi, vcc_hi, m0
	s_lshl_b32 vcc_hi, vcc_hi, 7
	v_add_u32_e32 v20, vcc_hi, v4
	v_add_u32_e32 v21, vcc_hi, v5
	v_add_u32_e32 v22, vcc_hi, v6
	v_add_u32_e32 v23, vcc_hi, v7
	v_add_u32_e32 v24, vcc_hi, v8
	v_add_u32_e32 v25, vcc_hi, v9
	v_add_u32_e32 v26, vcc_hi, v10
	v_add_u32_e32 v27, vcc_hi, v11
	v_add_u32_e32 v28, vcc_hi, v12
	v_add_u32_e32 v29, vcc_hi, v13
	v_add_u32_e32 v30, vcc_hi, v14
	v_add_u32_e32 v31, vcc_hi, v15
	v_add_u32_e32 v32, vcc_hi, v16
	v_add_u32_e32 v33, vcc_hi, v17
	v_add_u32_e32 v34, vcc_hi, v18
	v_add_u32_e32 v35, vcc_hi, v19
	s_add_u32 vcc_lo, vcc_lo, 1
	s_barrier
	s_add_u32 m0, s100, 0x8000
	s_nop 0
	global_load_lds_dwordx4 v20, s[40:41]
	s_add_u32 m0, s100, 0x8400
	s_nop 0
	global_load_lds_dwordx4 v21, s[40:41]
	s_add_u32 m0, s100, 0x9000
	s_nop 0
	global_load_lds_dwordx4 v22, s[40:41]
	s_add_u32 m0, s100, 0x9400
	s_nop 0
	global_load_lds_dwordx4 v23, s[40:41]
	s_add_u32 m0, s100, 0xa000
	s_nop 0
	global_load_lds_dwordx4 v24, s[40:41]
	s_add_u32 m0, s100, 0xa400
	s_nop 0
	global_load_lds_dwordx4 v25, s[40:41]
	s_add_u32 m0, s100, 0xb000
	s_nop 0
	global_load_lds_dwordx4 v26, s[40:41]
	s_add_u32 m0, s100, 0xb400
	s_nop 0
	global_load_lds_dwordx4 v27, s[40:41]
	s_waitcnt vmcnt(8)
	s_barrier
	s_add_u32 m0, s100, 0xc000
	s_nop 0
	global_load_lds_dwordx4 v28, s[38:39]
	s_add_u32 m0, s100, 0xc400
	s_nop 0
	global_load_lds_dwordx4 v29, s[38:39]
	s_add_u32 m0, s100, 0xd000
	s_nop 0
	global_load_lds_dwordx4 v30, s[38:39]
	s_add_u32 m0, s100, 0xd400
	s_nop 0
	global_load_lds_dwordx4 v31, s[38:39]
	s_add_u32 m0, s100, 0xe000
	s_nop 0
	global_load_lds_dwordx4 v32, s[38:39]
	s_add_u32 m0, s100, 0xe400
	s_nop 0
	global_load_lds_dwordx4 v33, s[38:39]
	s_add_u32 m0, s100, 0xf000
	s_nop 0
	global_load_lds_dwordx4 v34, s[38:39]
	s_add_u32 m0, s100, 0xf400
	s_nop 0
	global_load_lds_dwordx4 v35, s[38:39]
	s_add_u32 s34, s34, 0x100
	s_addc_u32 s35, s35, 0
	s_add_i32 s55, s55, 2
	s_cmp_le_i32 s55, s47
	s_cbranch_scc1 .Lpc_ptop_4
	s_mov_b32 s53, s49
	s_mov_b32 s52, s1
	v_mov_b64_e32 v[146:147], v[142:143]
	v_mov_b64_e32 v[144:145], v[140:141]
	s_and_b64 vcc, exec, s[26:27]
	s_cbranch_vccz .Lpc_pnd_4
	s_waitcnt vmcnt(0)
	s_branch .LBB0_342

.Lpc_prod_1:
.Lpc_ptop_1:
	s_mov_b32 s42, s47
	s_cmp_lt_i32 s53, s47
	s_cbranch_scc1 .Lpc_pcur_1
	s_mov_b32 vcc_lo, 0
	s_cmp_lg_u64 s[30:31], 0
	s_cbranch_scc1 .Lpc_pnext_1
	v_readfirstlane_b32 s40, v144
	v_readfirstlane_b32 s41, v145
	v_readfirstlane_b32 s38, v146
	v_readfirstlane_b32 s39, v147
	s_branch .Lpc_pgo_1

.Lpc_pgo_1:
	s_nop 0
	s_sub_u32 s40, s40, s98
	s_subb_u32 s41, s41, 0
	s_sub_u32 s38, s38, s99
	s_subb_u32 s39, s39, 0
	s_bfe_u32 vcc_hi, s101, 0x80008
	s_add_u32 vcc_hi, vcc_hi, vcc_lo
	s_add_u32 m0, s42, -1
	s_and_b32 vcc_hi, vcc_hi, m0
	s_lshl_b32 vcc_hi, vcc_hi, 7
	v_add_u32_e32 v20, vcc_hi, v4
	v_add_u32_e32 v21, vcc_hi, v5
	v_add_u32_e32 v22, vcc_hi, v6
	v_add_u32_e32 v23, vcc_hi, v7
	v_add_u32_e32 v24, vcc_hi, v8
	v_add_u32_e32 v25, vcc_hi, v9
	v_add_u32_e32 v26, vcc_hi, v10
	v_add_u32_e32 v27, vcc_hi, v11
	v_add_u32_e32 v28, vcc_hi, v12
	v_add_u32_e32 v29, vcc_hi, v13
	v_add_u32_e32 v30, vcc_hi, v14
	v_add_u32_e32 v31, vcc_hi, v15
	v_add_u32_e32 v32, vcc_hi, v16
	v_add_u32_e32 v33, vcc_hi, v17
	v_add_u32_e32 v34, vcc_hi, v18
	v_add_u32_e32 v35, vcc_hi, v19
	s_add_u32 vcc_lo, vcc_lo, 1
	s_barrier
	s_add_u32 m0, s100, 0x0
	s_nop 0
	global_load_lds_dwordx4 v20, s[40:41]
	s_add_u32 m0, s100, 0x400
	s_nop 0
	global_load_lds_dwordx4 v21, s[40:41]
	s_add_u32 m0, s100, 0x1000
	s_nop 0
	global_load_lds_dwordx4 v22, s[40:41]
	s_add_u32 m0, s100, 0x1400
	s_nop 0
	global_load_lds_dwordx4 v23, s[40:41]
	s_add_u32 m0, s100, 0x2000
	s_nop 0
	global_load_lds_dwordx4 v24, s[40:41]
	s_add_u32 m0, s100, 0x2400
	s_nop 0
	global_load_lds_dwordx4 v25, s[40:41]
	s_add_u32 m0, s100, 0x3000
	s_nop 0
	global_load_lds_dwordx4 v26, s[40:41]
	s_add_u32 m0, s100, 0x3400
	s_nop 0
	global_load_lds_dwordx4 v27, s[40:41]
	s_waitcnt vmcnt(8)
	s_barrier
	s_add_u32 m0, s100, 0x4000
	s_nop 0
	global_load_lds_dwordx4 v28, s[38:39]
	s_add_u32 m0, s100, 0x4400
	s_nop 0
	global_load_lds_dwordx4 v29, s[38:39]
	s_add_u32 m0, s100, 0x5000
	s_nop 0
	global_load_lds_dwordx4 v30, s[38:39]
	s_add_u32 m0, s100, 0x5400
	s_nop 0
	global_load_lds_dwordx4 v31, s[38:39]
	s_add_u32 m0, s100, 0x6000
	s_nop 0
	global_load_lds_dwordx4 v32, s[38:39]
	s_add_u32 m0, s100, 0x6400
	s_nop 0
	global_load_lds_dwordx4 v33, s[38:39]
	s_add_u32 m0, s100, 0x7000
	s_nop 0
	global_load_lds_dwordx4 v34, s[38:39]
	s_add_u32 m0, s100, 0x7400
	s_nop 0
	global_load_lds_dwordx4 v35, s[38:39]
	s_bfe_u32 vcc_hi, s101, 0x80008
	s_add_u32 vcc_hi, vcc_hi, vcc_lo
	s_add_u32 m0, s42, -1
	s_and_b32 vcc_hi, vcc_hi, m0
	s_lshl_b32 vcc_hi, vcc_hi, 7
	v_add_u32_e32 v20, vcc_hi, v4
	v_add_u32_e32 v21, vcc_hi, v5
	v_add_u32_e32 v22, vcc_hi, v6
	v_add_u32_e32 v23, vcc_hi, v7
	v_add_u32_e32 v24, vcc_hi, v8
	v_add_u32_e32 v25, vcc_hi, v9
	v_add_u32_e32 v26, vcc_hi, v10
	v_add_u32_e32 v27, vcc_hi, v11
	v_add_u32_e32 v28, vcc_hi, v12
	v_add_u32_e32 v29, vcc_hi, v13
	v_add_u32_e32 v30, vcc_hi, v14
	v_add_u32_e32 v31, vcc_hi, v15
	v_add_u32_e32 v32, vcc_hi, v16
	v_add_u32_e32 v33, vcc_hi, v17
	v_add_u32_e32 v34, vcc_hi, v18
	v_add_u32_e32 v35, vcc_hi, v19
	s_add_u32 vcc_lo, vcc_lo, 1
	s_barrier
	s_add_u32 m0, s100, 0x8000
	s_nop 0
	global_load_lds_dwordx4 v20, s[40:41]
	s_add_u32 m0, s100, 0x8400
	s_nop 0
	global_load_lds_dwordx4 v21, s[40:41]
	s_add_u32 m0, s100, 0x9000
	s_nop 0
	global_load_lds_dwordx4 v22, s[40:41]
	s_add_u32 m0, s100, 0x9400
	s_nop 0
	global_load_lds_dwordx4 v23, s[40:41]
	s_add_u32 m0, s100, 0xa000
	s_nop 0
	global_load_lds_dwordx4 v24, s[40:41]
	s_add_u32 m0, s100, 0xa400
	s_nop 0
	global_load_lds_dwordx4 v25, s[40:41]
	s_add_u32 m0, s100, 0xb000
	s_nop 0
	global_load_lds_dwordx4 v26, s[40:41]
	s_add_u32 m0, s100, 0xb400
	s_nop 0
	global_load_lds_dwordx4 v27, s[40:41]
	s_waitcnt vmcnt(8)
	s_barrier
	s_add_u32 m0, s100, 0xc000
	s_nop 0
	global_load_lds_dwordx4 v28, s[38:39]
	s_add_u32 m0, s100, 0xc400
	s_nop 0
	global_load_lds_dwordx4 v29, s[38:39]
	s_add_u32 m0, s100, 0xd000
	s_nop 0
	global_load_lds_dwordx4 v30, s[38:39]
	s_add_u32 m0, s100, 0xd400
	s_nop 0
	global_load_lds_dwordx4 v31, s[38:39]
	s_add_u32 m0, s100, 0xe000
	s_nop 0
	global_load_lds_dwordx4 v32, s[38:39]
	s_add_u32 m0, s100, 0xe400
	s_nop 0
	global_load_lds_dwordx4 v33, s[38:39]
	s_add_u32 m0, s100, 0xf000
	s_nop 0
	global_load_lds_dwordx4 v34, s[38:39]
	s_add_u32 m0, s100, 0xf400
	s_nop 0
	global_load_lds_dwordx4 v35, s[38:39]
	s_add_u32 s34, s34, 0x100
	s_addc_u32 s35, s35, 0
	s_add_i32 s53, s53, 2
	s_cmp_le_i32 s53, s47
	s_cbranch_scc1 .Lpc_ptop_1
	s_movk_i32 s4, 0x3100
	s_mov_b32 s52, s48
	s_mov_b32 s49, s1
	s_and_b64 vcc, exec, s[26:27]
	v_mov_b64_e32 v[146:147], v[142:143]
	v_mov_b64_e32 v[144:145], v[140:141]
	s_cbranch_vccz .Lpc_pnd_1
	s_waitcnt vmcnt(0)
	s_branch .LBB0_965
